# G5 K-loop only: one s_barrier per section per wave half (wr0 keeps pre-MFMA, wr1 keeps post-MFMA barriers), start/tile alignment barriers dropped
# baseline (speedup 1.0000x reference)
.LBB0_848:
	s_or_b64 exec, exec, s[8:9]
	v_readlane_b32 s4, v255, 11
	s_mov_b64 s[8:9], s[0:1]
	v_mov_b32_e32 v0, v232
	s_lshl_b32 s14, s50, 12
	v_mov_b32_e32 v150, v232
	v_readlane_b32 s5, v255, 12
	s_waitcnt lgkmcnt(0)
	s_ashr_i32 s15, s14, 31
	s_andn2_b64 vcc, exec, s[4:5]
	v_readfirstlane_b32 s20, v150
	s_cbranch_vccnz .Lg5_skipbar
	v_lshlrev_b32_e32 v2, 4, v150
	v_add_u32_e32 v3, 0x2000, v2
	v_ashrrev_i32_e32 v0, 31, v3
	v_lshrrev_b32_e32 v0, 22, v0
	v_add_u32_e32 v0, v3, v0
	v_ashrrev_i32_e32 v0, 10, v0
	s_load_dwordx2 s[12:13], s[8:9], 0x90
	v_mul_i32_i24_e32 v4, 0x400, v0
	v_sub_u32_e32 v3, v3, v4
	v_lshrrev_b32_e32 v4, 4, v3
	v_bitop3_b32 v3, v4, v3, 32 bitop3:0x6c
	v_ashrrev_i32_e32 v4, 31, v3
	s_waitcnt lgkmcnt(0)
	s_add_u32 s42, s12, 0x4200000
	v_lshrrev_b32_e32 v4, 26, v4
	s_addc_u32 s43, s13, 0
	v_add_u32_e32 v4, v3, v4
	v_lshlrev_b32_e32 v5, 3, v0
	s_add_u32 s4, s12, s84
	v_readlane_b32 s5, v255, 51
	v_ashrrev_i32_e32 v10, 6, v4
	v_and_b32_e32 v5, -16, v5
	s_addc_u32 s5, s13, s5
	v_add_u32_e32 v5, v10, v5
	s_add_u32 s44, s4, 0x1100000
	v_and_b32_e32 v6, 3, v10
	s_mov_b32 s4, 0x1fffe0
	v_lshrrev_b32_e32 v7, 2, v5
	v_lshlrev_b32_e32 v8, 1, v5
	v_and_b32_e32 v4, 0xc0, v4
	v_and_or_b32 v6, v5, s4, v6
	v_and_b32_e32 v7, 4, v7
	v_and_b32_e32 v8, 24, v8
	v_sub_u32_e32 v3, v3, v4
	v_or3_b32 v6, v6, v7, v8
	v_lshlrev_b32_e32 v7, 5, v0
	v_ashrrev_i16_sdwa v3, v247, sext(v3) dst_sel:DWORD dst_unused:UNUSED_PAD src0_sel:DWORD src1_sel:BYTE_0
	v_and_b32_e32 v7, 32, v7
	v_bfe_i32 v11, v3, 0, 16
	v_add_lshl_u32 v3, v7, v11, 1
	v_lshl_add_u32 v130, v6, 11, v3
	v_lshl_add_u32 v132, v5, 11, v3
	v_bfe_i32 v3, v150, 27, 1
	v_lshrrev_b32_e32 v3, 22, v3
	v_add_u32_e32 v3, v2, v3
	v_and_b32_e32 v3, 0xfffffc00, v3
	v_sub_u32_e32 v2, v2, v3
	v_lshrrev_b32_e32 v3, 4, v2
	v_bitop3_b32 v3, v3, v2, 32 bitop3:0x6c
	v_ashrrev_i32_e32 v2, 31, v2
	v_lshrrev_b32_e32 v2, 26, v2
	v_add_u32_e32 v2, v3, v2
	v_ashrrev_i32_e32 v12, 6, v2
	v_ashrrev_i32_e32 v2, 31, v150
	v_lshrrev_b32_e32 v2, 26, v2
	v_add_u32_e32 v2, v150, v2
	v_ashrrev_i32_e32 v13, 6, v2
	v_lshlrev_b32_e32 v2, 3, v13
	v_and_b32_e32 v2, -16, v2
	v_add_u32_e32 v2, v12, v2
	v_and_b32_e32 v4, 3, v12
	v_lshrrev_b32_e32 v5, 2, v2
	v_lshlrev_b32_e32 v6, 1, v2
	v_and_or_b32 v4, v2, s4, v4
	v_and_b32_e32 v5, 4, v5
	v_and_b32_e32 v6, 24, v6
	v_or3_b32 v4, v4, v5, v6
	v_mul_i32_i24_e32 v6, 64, v12
	s_addc_u32 s45, s5, 0
	s_ashr_i32 s8, s20, 6
	v_sub_u32_e32 v3, v3, v6
	s_ashr_i32 s9, s20, 8
	s_lshl_b32 s51, s8, 10
	v_lshlrev_b32_e32 v5, 5, v13
	v_ashrrev_i16_sdwa v3, v247, sext(v3) dst_sel:DWORD dst_unused:UNUSED_PAD src0_sel:DWORD src1_sel:BYTE_0
	v_readlane_b32 s4, v255, 21
	v_and_b32_e32 v5, 32, v5
	v_bfe_i32 v14, v3, 0, 16
	v_readlane_b32 s5, v255, 22
	s_add_u32 s34, s44, s4
	v_add_lshl_u32 v3, v5, v14, 1
	s_addc_u32 s35, s45, s5
	s_add_i32 s56, s51, 0
	v_lshl_add_u32 v134, v4, 11, v3
	s_add_i32 m0, s56, 0x10000
	v_readlane_b32 s4, v255, 19
	global_load_lds_dwordx4 v134, s[34:35]
	s_add_i32 m0, s56, 0x12000
	s_add_u32 s16, s34, 0x40000
	global_load_lds_dwordx4 v130, s[34:35]
	s_addc_u32 s17, s35, 0
	s_add_i32 m0, s56, 0x14000
	v_readlane_b32 s5, v255, 20
	global_load_lds_dwordx4 v134, s[16:17]
	s_add_i32 m0, s56, 0x16000
	s_add_u32 s30, s42, s4
	s_addc_u32 s31, s43, s5
	s_add_i32 s57, s56, 0x2000
	v_lshl_add_u32 v136, v2, 11, v3
	global_load_lds_dwordx4 v130, s[16:17]
	s_barrier
	s_mov_b32 m0, s56
	s_add_u32 s16, s30, 0x40000
	global_load_lds_dwordx4 v136, s[30:31]
	s_mov_b32 m0, s57
	s_addc_u32 s17, s31, 0
	s_add_i32 s58, s56, 0x4000
	global_load_lds_dwordx4 v132, s[30:31]
	s_mov_b32 m0, s58
	s_add_i32 s59, s56, 0x6000
	global_load_lds_dwordx4 v136, s[16:17]
	s_mov_b32 m0, s59
	v_mov_b32_e32 v135, v1
	global_load_lds_dwordx4 v132, s[16:17]
	v_mov_b32_e32 v131, v1
	v_mov_b32_e32 v137, v1
	v_mov_b32_e32 v133, v1
	s_cmp_eq_u32 s9, 1
	v_lshl_add_u64 v[8:9], s[34:35], 0, v[134:135]
	v_lshl_add_u64 v[6:7], s[34:35], 0, v[130:131]
	v_lshl_add_u64 v[2:3], s[30:31], 0, v[136:137]
	s_cselect_b64 s[16:17], -1, 0
	s_mov_b32 s101, s9
	s_cmp_lg_u32 s9, 1
	v_lshl_add_u64 v[4:5], s[30:31], 0, v[132:133]
	s_cbranch_scc1 .LBB0_851

.LBB0_861:
	s_add_u32 s4, s30, s34
	s_addc_u32 s5, s31, s35
	s_add_u32 s40, s4, 0x100
	s_addc_u32 s41, s5, 0
	s_add_u32 s38, s78, s34
	s_addc_u32 s39, s85, s35
	s_add_u32 s4, s4, 0x180
	s_addc_u32 s5, s5, 0
	s_add_i32 s65, 0, 0x10000
	s_add_i32 s87, 0, 0x14000
	v_add_u32_e32 v162, s65, v152
	v_add_u32_e32 v178, s87, v152
	ds_read_b128 v[146:149], v162
	ds_read_b128 v[154:157], v162 offset:1024
	ds_read_b128 v[158:161], v162 offset:2048
	ds_read_b128 v[162:165], v162 offset:3072
	ds_read_b128 v[166:169], v178
	ds_read_b128 v[170:173], v178 offset:1024
	ds_read_b128 v[174:177], v178 offset:2048
	ds_read_b128 v[178:181], v178 offset:3072
	s_cmpk_eq_i32 s34, 0x700
	s_cselect_b32 s37, s76, s5
	s_cselect_b32 s36, s75, s4
	s_cselect_b32 s39, s23, s39
	s_cselect_b32 s38, s74, s38
	s_cselect_b32 s41, s25, s41
	s_cselect_b32 s40, s73, s40
	v_lshl_add_u64 v[194:195], v[142:143], 0, s[34:35]
	s_add_i32 m0, s56, 0xc000
	ds_read_b128 v[182:185], v153
	ds_read_b128 v[186:189], v153 offset:1024
	ds_read_b128 v[190:193], v153 offset:2048
	ds_read_b128 v[202:205], v153 offset:3072
	ds_read_b128 v[206:209], v153 offset:4096
	ds_read_b128 v[210:213], v153 offset:5120
	ds_read_b128 v[214:217], v153 offset:6144
	ds_read_b128 v[218:221], v153 offset:7168
	global_load_lds_dwordx4 v[194:195], off
	v_lshl_add_u64 v[194:195], v[144:145], 0, s[34:35]
	s_add_i32 m0, s56, 0xe000
	s_nop 0
	global_load_lds_dwordx4 v[194:195], off
	s_waitcnt vmcnt(8)
	s_waitcnt lgkmcnt(0)
	s_setprio 1
	s_cmp_lg_u32 s101, 0
	s_cbranch_scc1 .Lpp_g5_0
	s_barrier
.Lpp_g5_0:
	v_mfma_f32_16x16x32_bf16 v[126:129], v[146:149], v[182:185], v[126:129]
	v_mfma_f32_16x16x32_bf16 v[122:125], v[158:161], v[182:185], v[122:125]
	v_mfma_f32_16x16x32_bf16 v[110:113], v[146:149], v[190:193], v[110:113]
	v_mfma_f32_16x16x32_bf16 v[106:109], v[158:161], v[190:193], v[106:109]
	v_mfma_f32_16x16x32_bf16 v[94:97], v[146:149], v[206:209], v[94:97]
	v_mfma_f32_16x16x32_bf16 v[90:93], v[158:161], v[206:209], v[90:93]
	v_mfma_f32_16x16x32_bf16 v[78:81], v[146:149], v[214:217], v[78:81]
	v_mfma_f32_16x16x32_bf16 v[74:77], v[158:161], v[214:217], v[74:77]
	v_mfma_f32_16x16x32_bf16 v[126:129], v[154:157], v[186:189], v[126:129]
	v_mfma_f32_16x16x32_bf16 v[122:125], v[162:165], v[186:189], v[122:125]
	v_mfma_f32_16x16x32_bf16 v[110:113], v[154:157], v[202:205], v[110:113]
	v_mfma_f32_16x16x32_bf16 v[106:109], v[162:165], v[202:205], v[106:109]
	v_mfma_f32_16x16x32_bf16 v[94:97], v[154:157], v[210:213], v[94:97]
	v_mfma_f32_16x16x32_bf16 v[90:93], v[162:165], v[210:213], v[90:93]
	v_mfma_f32_16x16x32_bf16 v[78:81], v[154:157], v[218:221], v[78:81]
	v_mfma_f32_16x16x32_bf16 v[74:77], v[162:165], v[218:221], v[74:77]
	v_mfma_f32_16x16x32_bf16 v[118:121], v[166:169], v[182:185], v[118:121]
	v_mfma_f32_16x16x32_bf16 v[114:117], v[174:177], v[182:185], v[114:117]
	v_mfma_f32_16x16x32_bf16 v[102:105], v[166:169], v[190:193], v[102:105]
	v_mfma_f32_16x16x32_bf16 v[98:101], v[174:177], v[190:193], v[98:101]
	v_mfma_f32_16x16x32_bf16 v[86:89], v[166:169], v[206:209], v[86:89]
	v_mfma_f32_16x16x32_bf16 v[82:85], v[174:177], v[206:209], v[82:85]
	v_mfma_f32_16x16x32_bf16 v[70:73], v[166:169], v[214:217], v[70:73]
	v_mfma_f32_16x16x32_bf16 v[66:69], v[174:177], v[214:217], v[66:69]
	v_mfma_f32_16x16x32_bf16 v[118:121], v[170:173], v[186:189], v[118:121]
	v_mfma_f32_16x16x32_bf16 v[114:117], v[178:181], v[186:189], v[114:117]
	v_mfma_f32_16x16x32_bf16 v[102:105], v[170:173], v[202:205], v[102:105]
	v_mfma_f32_16x16x32_bf16 v[98:101], v[178:181], v[202:205], v[98:101]
	v_mfma_f32_16x16x32_bf16 v[86:89], v[170:173], v[210:213], v[86:89]
	v_mfma_f32_16x16x32_bf16 v[82:85], v[178:181], v[210:213], v[82:85]
	v_mfma_f32_16x16x32_bf16 v[70:73], v[170:173], v[218:221], v[70:73]
	v_mfma_f32_16x16x32_bf16 v[66:69], v[178:181], v[218:221], v[66:69]
	s_cmp_eq_u32 s101, 0
	s_cbranch_scc1 .Lpp_g5_1
	s_barrier
.Lpp_g5_1:
	s_setprio 0
	s_add_i32 s4, s65, s51
	v_lshl_add_u64 v[194:195], s[38:39], 0, v[134:135]
	s_mov_b32 m0, s4
	ds_read_b128 v[182:185], v153 offset:16384
	ds_read_b128 v[186:189], v153 offset:17408
	ds_read_b128 v[190:193], v153 offset:18432
	ds_read_b128 v[202:205], v153 offset:19456
	ds_read_b128 v[206:209], v153 offset:20480
	ds_read_b128 v[210:213], v153 offset:21504
	ds_read_b128 v[214:217], v153 offset:22528
	ds_read_b128 v[218:221], v153 offset:23552
	global_load_lds_dwordx4 v[194:195], off
	s_add_i32 m0, s4, 0x2000
	s_add_u32 vcc_lo, s38, 0x40000
	v_lshl_add_u64 v[198:199], s[38:39], 0, v[130:131]
	s_addc_u32 vcc_hi, s39, 0
	s_add_i32 s4, s87, s51
	global_load_lds_dwordx4 v[198:199], off
	v_lshl_add_u64 v[222:223], vcc, 0, v[134:135]
	s_mov_b32 m0, s4
	s_nop 0
	global_load_lds_dwordx4 v[222:223], off
	v_lshl_add_u64 v[222:223], vcc, 0, v[130:131]
	s_add_i32 m0, s4, 0x2000
	s_nop 0
	global_load_lds_dwordx4 v[222:223], off
	v_lshl_add_u64 v[222:223], s[40:41], 0, v[136:137]
	s_mov_b32 m0, s56
	s_nop 0
	global_load_lds_dwordx4 v[222:223], off
	v_lshl_add_u64 v[222:223], s[40:41], 0, v[132:133]
	s_mov_b32 m0, s57
	s_nop 0
	global_load_lds_dwordx4 v[222:223], off
	s_waitcnt vmcnt(8)
	s_waitcnt lgkmcnt(0)
	s_setprio 1
	s_cmp_lg_u32 s101, 0
	s_cbranch_scc1 .Lpp_g5_2
	s_barrier
.Lpp_g5_2:
	v_mfma_f32_16x16x32_bf16 v[62:65], v[146:149], v[182:185], v[62:65]
	v_mfma_f32_16x16x32_bf16 v[58:61], v[158:161], v[182:185], v[58:61]
	v_mfma_f32_16x16x32_bf16 v[46:49], v[146:149], v[190:193], v[46:49]
	v_mfma_f32_16x16x32_bf16 v[42:45], v[158:161], v[190:193], v[42:45]
	v_mfma_f32_16x16x32_bf16 v[30:33], v[146:149], v[206:209], v[30:33]
	v_mfma_f32_16x16x32_bf16 v[26:29], v[158:161], v[206:209], v[26:29]
	v_mfma_f32_16x16x32_bf16 v[14:17], v[146:149], v[214:217], v[14:17]
	v_mfma_f32_16x16x32_bf16 v[10:13], v[158:161], v[214:217], v[10:13]
	v_mfma_f32_16x16x32_bf16 v[62:65], v[154:157], v[186:189], v[62:65]
	v_mfma_f32_16x16x32_bf16 v[58:61], v[162:165], v[186:189], v[58:61]
	v_mfma_f32_16x16x32_bf16 v[46:49], v[154:157], v[202:205], v[46:49]
	v_mfma_f32_16x16x32_bf16 v[42:45], v[162:165], v[202:205], v[42:45]
	v_mfma_f32_16x16x32_bf16 v[30:33], v[154:157], v[210:213], v[30:33]
	v_mfma_f32_16x16x32_bf16 v[26:29], v[162:165], v[210:213], v[26:29]
	v_mfma_f32_16x16x32_bf16 v[14:17], v[154:157], v[218:221], v[14:17]
	v_mfma_f32_16x16x32_bf16 v[10:13], v[162:165], v[218:221], v[10:13]
	v_mfma_f32_16x16x32_bf16 v[54:57], v[166:169], v[182:185], v[54:57]
	v_mfma_f32_16x16x32_bf16 v[50:53], v[174:177], v[182:185], v[50:53]
	v_mfma_f32_16x16x32_bf16 v[38:41], v[166:169], v[190:193], v[38:41]
	v_mfma_f32_16x16x32_bf16 v[34:37], v[174:177], v[190:193], v[34:37]
	v_mfma_f32_16x16x32_bf16 v[22:25], v[166:169], v[206:209], v[22:25]
	v_mfma_f32_16x16x32_bf16 v[18:21], v[174:177], v[206:209], v[18:21]
	v_mfma_f32_16x16x32_bf16 v[6:9], v[166:169], v[214:217], v[6:9]
	v_mfma_f32_16x16x32_bf16 v[2:5], v[174:177], v[214:217], v[2:5]
	v_mfma_f32_16x16x32_bf16 v[54:57], v[170:173], v[186:189], v[54:57]
	v_mfma_f32_16x16x32_bf16 v[50:53], v[178:181], v[186:189], v[50:53]
	v_mfma_f32_16x16x32_bf16 v[38:41], v[170:173], v[202:205], v[38:41]
	v_mfma_f32_16x16x32_bf16 v[34:37], v[178:181], v[202:205], v[34:37]
	v_mfma_f32_16x16x32_bf16 v[22:25], v[170:173], v[210:213], v[22:25]
	v_mfma_f32_16x16x32_bf16 v[18:21], v[178:181], v[210:213], v[18:21]
	v_mfma_f32_16x16x32_bf16 v[6:9], v[170:173], v[218:221], v[6:9]
	v_mfma_f32_16x16x32_bf16 v[2:5], v[178:181], v[218:221], v[2:5]
	s_cmp_eq_u32 s101, 0
	s_cbranch_scc1 .Lpp_g5_3
	s_barrier
.Lpp_g5_3:
	s_setprio 0
	s_add_i32 s4, 0, 0x18000
	s_add_i32 s5, 0, 0x1c000
	v_add_u32_e32 v162, s4, v152
	v_add_u32_e32 v178, s5, v152
	ds_read_b128 v[146:149], v162
	ds_read_b128 v[154:157], v162 offset:1024
	ds_read_b128 v[158:161], v162 offset:2048
	ds_read_b128 v[162:165], v162 offset:3072
	ds_read_b128 v[166:169], v178
	ds_read_b128 v[170:173], v178 offset:1024
	ds_read_b128 v[174:177], v178 offset:2048
	ds_read_b128 v[178:181], v178 offset:3072
	s_add_u32 s40, s40, 0x40000
	s_addc_u32 s41, s41, 0
	s_mov_b32 m0, s58
	v_lshl_add_u64 v[222:223], s[40:41], 0, v[136:137]
	ds_read_b128 v[182:185], v153 offset:32768
	ds_read_b128 v[186:189], v153 offset:33792
	ds_read_b128 v[190:193], v153 offset:34816
	ds_read_b128 v[202:205], v153 offset:35840
	ds_read_b128 v[206:209], v153 offset:36864
	ds_read_b128 v[210:213], v153 offset:37888
	ds_read_b128 v[214:217], v153 offset:38912
	ds_read_b128 v[218:221], v153 offset:39936
	global_load_lds_dwordx4 v[222:223], off
	v_lshl_add_u64 v[222:223], s[40:41], 0, v[132:133]
	s_mov_b32 m0, s59
	s_nop 0
	global_load_lds_dwordx4 v[222:223], off
	s_waitcnt vmcnt(8)
	s_waitcnt lgkmcnt(0)
	s_setprio 1
	s_cmp_lg_u32 s101, 0
	s_cbranch_scc1 .Lpp_g5_4
	s_barrier

.Lpp_g5_5:
	s_setprio 0
	s_add_i32 s4, s4, s51
	v_lshl_add_u64 v[194:195], v[194:195], 0, s[90:91]
	s_mov_b32 m0, s4
	ds_read_b128 v[182:185], v153 offset:49152
	ds_read_b128 v[186:189], v153 offset:50176
	ds_read_b128 v[190:193], v153 offset:51200
	ds_read_b128 v[202:205], v153 offset:52224
	ds_read_b128 v[206:209], v153 offset:53248
	ds_read_b128 v[210:213], v153 offset:54272
	ds_read_b128 v[214:217], v153 offset:55296
	ds_read_b128 v[218:221], v153 offset:56320
	global_load_lds_dwordx4 v[194:195], off
	s_add_i32 m0, s4, 0x2000
	s_add_u32 s38, s38, 0x40080
	v_lshl_add_u64 v[194:195], v[198:199], 0, s[90:91]
	s_addc_u32 s39, s39, 0
	s_add_i32 s4, s5, s51
	global_load_lds_dwordx4 v[194:195], off
	v_lshl_add_u64 v[194:195], s[38:39], 0, v[134:135]
	s_mov_b32 m0, s4
	s_nop 0
	global_load_lds_dwordx4 v[194:195], off
	v_lshl_add_u64 v[194:195], s[38:39], 0, v[130:131]
	s_add_i32 m0, s4, 0x2000
	s_nop 0
	global_load_lds_dwordx4 v[194:195], off
	v_lshl_add_u64 v[194:195], s[36:37], 0, v[136:137]
	s_mov_b32 m0, s68
	s_nop 0
	global_load_lds_dwordx4 v[194:195], off
	v_lshl_add_u64 v[194:195], s[36:37], 0, v[132:133]
	s_mov_b32 m0, s69
	s_nop 0
	global_load_lds_dwordx4 v[194:195], off
	s_waitcnt vmcnt(8)
	s_waitcnt lgkmcnt(0)
	s_setprio 1
	s_cmp_lg_u32 s101, 0
	s_cbranch_scc1 .Lpp_g5_6
	s_barrier

.Lpp_g5_7:
	s_setprio 0
	s_add_i32 s86, s86, 2
	s_add_u32 s34, s34, 0x100
	s_addc_u32 s35, s35, 0
	s_cmp_gt_u32 s86, 13
	s_cbranch_scc0 .LBB0_861
	s_and_b64 vcc, exec, s[20:21]
	s_cbranch_vccz .LBB0_864
.LBB0_864:
	v_lshl_add_u32 v142, s72, 8, v151
	v_ashrrev_i32_e32 v143, 31, v142
	v_lshl_add_u64 v[160:161], v[142:143], 2, s[10:11]
	global_load_dword v162, v[160:161], off
	global_load_dword v163, v[160:161], off offset:64
	global_load_dword v159, v[160:161], off offset:128
	global_load_dword v158, v[160:161], off offset:192
	global_load_dword v157, v[160:161], off offset:512
	global_load_dword v156, v[160:161], off offset:576
	global_load_dword v155, v[160:161], off offset:640
	global_load_dword v154, v[160:161], off offset:704
	s_lshl_b32 s30, s71, 8
	v_or_b32_e32 v148, 16, v142
	v_or_b32_e32 v146, 32, v142
	v_or_b32_e32 v144, 48, v142
	s_ashr_i32 s31, s30, 31
	v_lshlrev_b64 v[142:143], 13, v[142:143]
	v_ashrrev_i32_e32 v149, 31, v148
	v_lshl_add_u64 v[142:143], s[18:19], 0, v[142:143]
	s_lshl_b64 s[30:31], s[30:31], 1
	v_lshl_add_u64 v[142:143], v[142:143], 0, s[30:31]
	v_ashrrev_i32_e32 v147, 31, v146
	v_lshl_add_u64 v[142:143], v[142:143], 0, v[0:1]
	v_ashrrev_i32_e32 v145, 31, v144
	s_waitcnt vmcnt(0)
	v_fmamk_f32 v160, v162, 0x3a800000, v233
	v_cmp_gt_f32_e32 vcc, s82, v160
	v_mul_f32_e32 v161, 0x4b800000, v160
	s_nop 0
	v_cndmask_b32_e32 v160, v160, v161, vcc
	v_rsq_f32_e32 v160, v160
	s_nop 0
	v_mul_f32_e32 v161, 0x45800000, v160
	v_cndmask_b32_e32 v160, v160, v161, vcc
	v_pk_mul_f32 v[120:121], v[120:121], v[160:161] op_sel_hi:[1,0]
	v_pk_mul_f32 v[118:119], v[118:119], v[160:161] op_sel_hi:[1,0]
	v_pk_mul_f32 v[114:115], v[114:115], v[160:161] op_sel_hi:[1,0]
	v_max_f32_e32 v118, 0, v118
	v_max_f32_e32 v119, 0, v119
	v_max_f32_e32 v120, 0, v120
	v_max_f32_e32 v121, 0, v121
	v_max_f32_e32 v114, 0, v114
	v_max_f32_e32 v115, 0, v115
	v_pk_mul_f32 v[118:119], v[118:119], v[118:119]
	v_pk_mul_f32 v[120:121], v[120:121], v[120:121]
	v_pk_mul_f32 v[116:117], v[116:117], v[160:161] op_sel_hi:[1,0]
	v_pk_mul_f32 v[114:115], v[114:115], v[114:115]
	v_cvt_pk_bf16_f32 v118, v118, v119
	v_cvt_pk_bf16_f32 v119, v120, v121
	v_cvt_pk_bf16_f32 v120, v114, v115
	v_max_f32_e32 v114, 0, v116
	v_max_f32_e32 v115, 0, v117
	v_pk_mul_f32 v[114:115], v[114:115], v[114:115]
	v_pk_mul_f32 v[128:129], v[128:129], v[160:161] op_sel_hi:[1,0]
	v_cvt_pk_bf16_f32 v121, v114, v115
	v_fmamk_f32 v114, v163, 0x3a800000, v233
	v_cmp_gt_f32_e32 vcc, s82, v114
	v_mul_f32_e32 v115, 0x4b800000, v114
	v_pk_mul_f32 v[126:127], v[126:127], v[160:161] op_sel_hi:[1,0]
	v_cndmask_b32_e32 v114, v114, v115, vcc
	v_rsq_f32_e32 v114, v114
	v_pk_mul_f32 v[122:123], v[122:123], v[160:161] op_sel_hi:[1,0]
	v_max_f32_e32 v126, 0, v126
	v_max_f32_e32 v127, 0, v127
	v_mul_f32_e32 v115, 0x45800000, v114
	v_cndmask_b32_e32 v114, v114, v115, vcc
	v_pk_mul_f32 v[104:105], v[104:105], v[114:115] op_sel_hi:[1,0]
	v_pk_mul_f32 v[102:103], v[102:103], v[114:115] op_sel_hi:[1,0]
	v_pk_mul_f32 v[98:99], v[98:99], v[114:115] op_sel_hi:[1,0]
	v_max_f32_e32 v102, 0, v102
	v_max_f32_e32 v103, 0, v103
	v_max_f32_e32 v104, 0, v104
	v_max_f32_e32 v105, 0, v105
	v_max_f32_e32 v98, 0, v98
	v_max_f32_e32 v99, 0, v99
	v_pk_mul_f32 v[102:103], v[102:103], v[102:103]
	v_pk_mul_f32 v[104:105], v[104:105], v[104:105]
	v_pk_mul_f32 v[100:101], v[100:101], v[114:115] op_sel_hi:[1,0]
	v_pk_mul_f32 v[98:99], v[98:99], v[98:99]
	v_cvt_pk_bf16_f32 v102, v102, v103
	v_cvt_pk_bf16_f32 v103, v104, v105
	v_cvt_pk_bf16_f32 v104, v98, v99
	v_max_f32_e32 v98, 0, v100
	v_max_f32_e32 v99, 0, v101
	v_pk_mul_f32 v[98:99], v[98:99], v[98:99]
	v_max_f32_e32 v128, 0, v128
	v_cvt_pk_bf16_f32 v105, v98, v99
	v_fmamk_f32 v98, v159, 0x3a800000, v233
	v_cmp_gt_f32_e32 vcc, s82, v98
	v_mul_f32_e32 v99, 0x4b800000, v98
	v_max_f32_e32 v129, 0, v129
	v_cndmask_b32_e32 v98, v98, v99, vcc
	v_rsq_f32_e32 v98, v98
	v_max_f32_e32 v122, 0, v122
	v_max_f32_e32 v123, 0, v123
	v_pk_mul_f32 v[126:127], v[126:127], v[126:127]
	v_mul_f32_e32 v99, 0x45800000, v98
	v_cndmask_b32_e32 v98, v98, v99, vcc
	v_pk_mul_f32 v[88:89], v[88:89], v[98:99] op_sel_hi:[1,0]
	v_pk_mul_f32 v[86:87], v[86:87], v[98:99] op_sel_hi:[1,0]
	v_pk_mul_f32 v[82:83], v[82:83], v[98:99] op_sel_hi:[1,0]
	v_max_f32_e32 v86, 0, v86
	v_max_f32_e32 v87, 0, v87
	v_max_f32_e32 v88, 0, v88
	v_max_f32_e32 v89, 0, v89
	v_max_f32_e32 v82, 0, v82
	v_max_f32_e32 v83, 0, v83
	v_pk_mul_f32 v[86:87], v[86:87], v[86:87]
	v_pk_mul_f32 v[88:89], v[88:89], v[88:89]
	v_pk_mul_f32 v[84:85], v[84:85], v[98:99] op_sel_hi:[1,0]
	v_pk_mul_f32 v[82:83], v[82:83], v[82:83]
	v_cvt_pk_bf16_f32 v86, v86, v87
	v_cvt_pk_bf16_f32 v87, v88, v89
	v_cvt_pk_bf16_f32 v88, v82, v83
	v_max_f32_e32 v82, 0, v84
	v_max_f32_e32 v83, 0, v85
	v_pk_mul_f32 v[82:83], v[82:83], v[82:83]
	v_pk_mul_f32 v[128:129], v[128:129], v[128:129]
	v_cvt_pk_bf16_f32 v89, v82, v83
	v_fmamk_f32 v82, v158, 0x3a800000, v233
	v_cmp_gt_f32_e32 vcc, s82, v82
	v_mul_f32_e32 v83, 0x4b800000, v82
	v_pk_mul_f32 v[124:125], v[124:125], v[160:161] op_sel_hi:[1,0]
	v_cndmask_b32_e32 v82, v82, v83, vcc
	v_rsq_f32_e32 v82, v82
	v_pk_mul_f32 v[122:123], v[122:123], v[122:123]
	v_pk_mul_f32 v[112:113], v[112:113], v[114:115] op_sel_hi:[1,0]
	v_pk_mul_f32 v[110:111], v[110:111], v[114:115] op_sel_hi:[1,0]
	v_mul_f32_e32 v83, 0x45800000, v82
	v_cndmask_b32_e32 v82, v82, v83, vcc
	v_pk_mul_f32 v[72:73], v[72:73], v[82:83] op_sel_hi:[1,0]
	v_pk_mul_f32 v[70:71], v[70:71], v[82:83] op_sel_hi:[1,0]
	v_pk_mul_f32 v[66:67], v[66:67], v[82:83] op_sel_hi:[1,0]
	v_max_f32_e32 v70, 0, v70
	v_max_f32_e32 v71, 0, v71
	v_max_f32_e32 v72, 0, v72
	v_max_f32_e32 v73, 0, v73
	v_max_f32_e32 v66, 0, v66
	v_max_f32_e32 v67, 0, v67
	v_pk_mul_f32 v[70:71], v[70:71], v[70:71]
	v_pk_mul_f32 v[72:73], v[72:73], v[72:73]
	v_pk_mul_f32 v[68:69], v[68:69], v[82:83] op_sel_hi:[1,0]
	v_pk_mul_f32 v[66:67], v[66:67], v[66:67]
	v_cvt_pk_bf16_f32 v70, v70, v71
	v_cvt_pk_bf16_f32 v71, v72, v73
	v_cvt_pk_bf16_f32 v72, v66, v67
	v_max_f32_e32 v66, 0, v68
	v_max_f32_e32 v67, 0, v69
	v_pk_mul_f32 v[66:67], v[66:67], v[66:67]
	v_pk_mul_f32 v[106:107], v[106:107], v[114:115] op_sel_hi:[1,0]
	v_cvt_pk_bf16_f32 v73, v66, v67
	v_fmamk_f32 v66, v157, 0x3a800000, v233
	v_cmp_gt_f32_e32 vcc, s82, v66
	v_mul_f32_e32 v67, 0x4b800000, v66
	v_cvt_pk_bf16_f32 v126, v126, v127
	v_cndmask_b32_e32 v66, v66, v67, vcc
	v_rsq_f32_e32 v66, v66
	v_cvt_pk_bf16_f32 v127, v128, v129
	v_cvt_pk_bf16_f32 v128, v122, v123
	v_max_f32_e32 v122, 0, v124
	v_mul_f32_e32 v67, 0x45800000, v66
	v_cndmask_b32_e32 v66, v66, v67, vcc
	v_pk_mul_f32 v[56:57], v[56:57], v[66:67] op_sel_hi:[1,0]
	v_pk_mul_f32 v[54:55], v[54:55], v[66:67] op_sel_hi:[1,0]
	v_pk_mul_f32 v[50:51], v[50:51], v[66:67] op_sel_hi:[1,0]
	v_max_f32_e32 v54, 0, v54
	v_max_f32_e32 v55, 0, v55
	v_max_f32_e32 v56, 0, v56
	v_max_f32_e32 v57, 0, v57
	v_max_f32_e32 v50, 0, v50
	v_max_f32_e32 v51, 0, v51
	v_pk_mul_f32 v[54:55], v[54:55], v[54:55]
	v_pk_mul_f32 v[56:57], v[56:57], v[56:57]
	v_pk_mul_f32 v[52:53], v[52:53], v[66:67] op_sel_hi:[1,0]
	v_pk_mul_f32 v[50:51], v[50:51], v[50:51]
	v_cvt_pk_bf16_f32 v54, v54, v55
	v_cvt_pk_bf16_f32 v55, v56, v57
	v_cvt_pk_bf16_f32 v56, v50, v51
	v_max_f32_e32 v50, 0, v52
	v_max_f32_e32 v51, 0, v53
	v_pk_mul_f32 v[50:51], v[50:51], v[50:51]
	v_max_f32_e32 v123, 0, v125
	v_cvt_pk_bf16_f32 v57, v50, v51
	v_fmamk_f32 v50, v156, 0x3a800000, v233
	v_cmp_gt_f32_e32 vcc, s82, v50
	v_mul_f32_e32 v51, 0x4b800000, v50
	v_max_f32_e32 v110, 0, v110
	v_cndmask_b32_e32 v50, v50, v51, vcc
	v_rsq_f32_e32 v50, v50
	v_max_f32_e32 v111, 0, v111
	v_max_f32_e32 v112, 0, v112
	v_max_f32_e32 v113, 0, v113
	v_mul_f32_e32 v51, 0x45800000, v50
	v_cndmask_b32_e32 v50, v50, v51, vcc
	v_pk_mul_f32 v[40:41], v[40:41], v[50:51] op_sel_hi:[1,0]
	v_pk_mul_f32 v[38:39], v[38:39], v[50:51] op_sel_hi:[1,0]
	v_pk_mul_f32 v[34:35], v[34:35], v[50:51] op_sel_hi:[1,0]
	v_max_f32_e32 v38, 0, v38
	v_max_f32_e32 v39, 0, v39
	v_max_f32_e32 v40, 0, v40
	v_max_f32_e32 v41, 0, v41
	v_max_f32_e32 v34, 0, v34
	v_max_f32_e32 v35, 0, v35
	v_pk_mul_f32 v[38:39], v[38:39], v[38:39]
	v_pk_mul_f32 v[40:41], v[40:41], v[40:41]
	v_pk_mul_f32 v[36:37], v[36:37], v[50:51] op_sel_hi:[1,0]
	v_pk_mul_f32 v[34:35], v[34:35], v[34:35]
	v_cvt_pk_bf16_f32 v38, v38, v39
	v_cvt_pk_bf16_f32 v39, v40, v41
	v_cvt_pk_bf16_f32 v40, v34, v35
	v_max_f32_e32 v34, 0, v36
	v_max_f32_e32 v35, 0, v37
	v_pk_mul_f32 v[34:35], v[34:35], v[34:35]
	v_max_f32_e32 v106, 0, v106
	v_cvt_pk_bf16_f32 v41, v34, v35
	v_fmamk_f32 v34, v155, 0x3a800000, v233
	v_cmp_gt_f32_e32 vcc, s82, v34
	v_mul_f32_e32 v35, 0x4b800000, v34
	v_max_f32_e32 v107, 0, v107
	v_cndmask_b32_e32 v34, v34, v35, vcc
	v_rsq_f32_e32 v34, v34
	v_pk_mul_f32 v[122:123], v[122:123], v[122:123]
	v_lshlrev_b64 v[116:117], 13, v[148:149]
	v_pk_mul_f32 v[110:111], v[110:111], v[110:111]
	v_mul_f32_e32 v35, 0x45800000, v34
	v_cndmask_b32_e32 v34, v34, v35, vcc
	v_pk_mul_f32 v[24:25], v[24:25], v[34:35] op_sel_hi:[1,0]
	v_pk_mul_f32 v[22:23], v[22:23], v[34:35] op_sel_hi:[1,0]
	v_pk_mul_f32 v[18:19], v[18:19], v[34:35] op_sel_hi:[1,0]
	v_max_f32_e32 v22, 0, v22
	v_max_f32_e32 v23, 0, v23
	v_max_f32_e32 v24, 0, v24
	v_max_f32_e32 v25, 0, v25
	v_max_f32_e32 v18, 0, v18
	v_max_f32_e32 v19, 0, v19
	v_pk_mul_f32 v[22:23], v[22:23], v[22:23]
	v_pk_mul_f32 v[24:25], v[24:25], v[24:25]
	v_pk_mul_f32 v[20:21], v[20:21], v[34:35] op_sel_hi:[1,0]
	v_pk_mul_f32 v[18:19], v[18:19], v[18:19]
	v_cvt_pk_bf16_f32 v22, v22, v23
	v_cvt_pk_bf16_f32 v23, v24, v25
	v_cvt_pk_bf16_f32 v24, v18, v19
	v_max_f32_e32 v18, 0, v20
	v_max_f32_e32 v19, 0, v21
	v_pk_mul_f32 v[112:113], v[112:113], v[112:113]
	v_pk_mul_f32 v[108:109], v[108:109], v[114:115] op_sel_hi:[1,0]
	v_pk_mul_f32 v[106:107], v[106:107], v[106:107]
	v_pk_mul_f32 v[96:97], v[96:97], v[98:99] op_sel_hi:[1,0]
	v_pk_mul_f32 v[94:95], v[94:95], v[98:99] op_sel_hi:[1,0]
	v_pk_mul_f32 v[90:91], v[90:91], v[98:99] op_sel_hi:[1,0]
	v_pk_mul_f32 v[18:19], v[18:19], v[18:19]
	v_cvt_pk_bf16_f32 v129, v122, v123
	global_store_dwordx4 v[142:143], v[126:129], off offset:0 sc1
	s_nop 1
	v_lshl_add_u64 v[116:117], s[18:19], 0, v[116:117]
	v_cvt_pk_bf16_f32 v110, v110, v111
	v_cvt_pk_bf16_f32 v111, v112, v113
	v_cvt_pk_bf16_f32 v112, v106, v107
	v_max_f32_e32 v106, 0, v108
	v_max_f32_e32 v107, 0, v109
	v_max_f32_e32 v94, 0, v94
	v_max_f32_e32 v95, 0, v95
	v_max_f32_e32 v96, 0, v96
	v_max_f32_e32 v97, 0, v97
	v_max_f32_e32 v90, 0, v90
	v_max_f32_e32 v91, 0, v91
	v_cvt_pk_bf16_f32 v25, v18, v19
	v_fmamk_f32 v18, v154, 0x3a800000, v233
	global_store_dwordx4 v[142:143], v[118:121], off offset:0x100 sc1
	s_nop 1
	v_lshl_add_u64 v[116:117], v[116:117], 0, s[30:31]
	v_pk_mul_f32 v[106:107], v[106:107], v[106:107]
	v_lshlrev_b64 v[100:101], 13, v[146:147]
	v_pk_mul_f32 v[94:95], v[94:95], v[94:95]
	v_pk_mul_f32 v[96:97], v[96:97], v[96:97]
	v_pk_mul_f32 v[92:93], v[92:93], v[98:99] op_sel_hi:[1,0]
	v_pk_mul_f32 v[90:91], v[90:91], v[90:91]
	v_pk_mul_f32 v[80:81], v[80:81], v[82:83] op_sel_hi:[1,0]
	v_pk_mul_f32 v[78:79], v[78:79], v[82:83] op_sel_hi:[1,0]
	v_pk_mul_f32 v[74:75], v[74:75], v[82:83] op_sel_hi:[1,0]
	v_cmp_gt_f32_e32 vcc, s82, v18
	v_mul_f32_e32 v19, 0x4b800000, v18
	v_lshl_add_u64 v[116:117], v[116:117], 0, v[0:1]
	v_cvt_pk_bf16_f32 v113, v106, v107
	global_store_dwordx4 v[116:117], v[110:113], off offset:0 sc1
	s_nop 1
	v_lshl_add_u64 v[100:101], s[18:19], 0, v[100:101]
	v_cvt_pk_bf16_f32 v94, v94, v95
	v_cvt_pk_bf16_f32 v95, v96, v97
	v_cvt_pk_bf16_f32 v96, v90, v91
	v_max_f32_e32 v90, 0, v92
	v_max_f32_e32 v91, 0, v93
	v_max_f32_e32 v78, 0, v78
	v_max_f32_e32 v79, 0, v79
	v_max_f32_e32 v80, 0, v80
	v_max_f32_e32 v81, 0, v81
	v_max_f32_e32 v74, 0, v74
	v_max_f32_e32 v75, 0, v75
	v_cndmask_b32_e32 v18, v18, v19, vcc
	global_store_dwordx4 v[116:117], v[102:105], off offset:0x100 sc1
	s_nop 1
	v_lshl_add_u64 v[100:101], v[100:101], 0, s[30:31]
	v_pk_mul_f32 v[90:91], v[90:91], v[90:91]
	v_lshlrev_b64 v[84:85], 13, v[144:145]
	v_pk_mul_f32 v[78:79], v[78:79], v[78:79]
	v_pk_mul_f32 v[80:81], v[80:81], v[80:81]
	v_pk_mul_f32 v[76:77], v[76:77], v[82:83] op_sel_hi:[1,0]
	v_pk_mul_f32 v[74:75], v[74:75], v[74:75]
	v_pk_mul_f32 v[64:65], v[64:65], v[66:67] op_sel_hi:[1,0]
	v_pk_mul_f32 v[62:63], v[62:63], v[66:67] op_sel_hi:[1,0]
	v_pk_mul_f32 v[58:59], v[58:59], v[66:67] op_sel_hi:[1,0]
	v_rsq_f32_e32 v18, v18
	v_lshl_add_u64 v[100:101], v[100:101], 0, v[0:1]
	v_cvt_pk_bf16_f32 v97, v90, v91
	global_store_dwordx4 v[100:101], v[94:97], off offset:0 sc1
	s_nop 1
	v_lshl_add_u64 v[84:85], s[18:19], 0, v[84:85]
	v_cvt_pk_bf16_f32 v78, v78, v79
	v_cvt_pk_bf16_f32 v79, v80, v81
	v_cvt_pk_bf16_f32 v80, v74, v75
	v_max_f32_e32 v74, 0, v76
	v_max_f32_e32 v75, 0, v77
	v_max_f32_e32 v62, 0, v62
	v_max_f32_e32 v63, 0, v63
	v_max_f32_e32 v64, 0, v64
	v_max_f32_e32 v65, 0, v65
	v_max_f32_e32 v58, 0, v58
	v_max_f32_e32 v59, 0, v59
	global_store_dwordx4 v[100:101], v[86:89], off offset:0x100 sc1
	s_nop 1
	v_lshl_add_u64 v[84:85], v[84:85], 0, s[30:31]
	v_pk_mul_f32 v[74:75], v[74:75], v[74:75]
	v_pk_mul_f32 v[62:63], v[62:63], v[62:63]
	v_pk_mul_f32 v[64:65], v[64:65], v[64:65]
	v_pk_mul_f32 v[60:61], v[60:61], v[66:67] op_sel_hi:[1,0]
	v_pk_mul_f32 v[58:59], v[58:59], v[58:59]
	v_pk_mul_f32 v[48:49], v[48:49], v[50:51] op_sel_hi:[1,0]
	v_pk_mul_f32 v[46:47], v[46:47], v[50:51] op_sel_hi:[1,0]
	v_pk_mul_f32 v[42:43], v[42:43], v[50:51] op_sel_hi:[1,0]
	v_lshl_add_u64 v[84:85], v[84:85], 0, v[0:1]
	v_cvt_pk_bf16_f32 v81, v74, v75
	global_store_dwordx4 v[84:85], v[78:81], off offset:0 sc1
	s_nop 1
	v_cvt_pk_bf16_f32 v62, v62, v63
	v_cvt_pk_bf16_f32 v63, v64, v65
	v_cvt_pk_bf16_f32 v64, v58, v59
	v_max_f32_e32 v58, 0, v60
	v_max_f32_e32 v59, 0, v61
	v_max_f32_e32 v46, 0, v46
	v_max_f32_e32 v47, 0, v47
	v_max_f32_e32 v48, 0, v48
	v_max_f32_e32 v49, 0, v49
	v_max_f32_e32 v42, 0, v42
	v_max_f32_e32 v43, 0, v43
	global_store_dwordx4 v[84:85], v[70:73], off offset:0x100 sc1
	s_nop 1
	s_mov_b64 s[30:31], 0x100000
	v_pk_mul_f32 v[58:59], v[58:59], v[58:59]
	v_pk_mul_f32 v[46:47], v[46:47], v[46:47]
	v_pk_mul_f32 v[48:49], v[48:49], v[48:49]
	v_pk_mul_f32 v[44:45], v[44:45], v[50:51] op_sel_hi:[1,0]
	v_pk_mul_f32 v[42:43], v[42:43], v[42:43]
	v_pk_mul_f32 v[32:33], v[32:33], v[34:35] op_sel_hi:[1,0]
	v_pk_mul_f32 v[30:31], v[30:31], v[34:35] op_sel_hi:[1,0]
	v_pk_mul_f32 v[26:27], v[26:27], v[34:35] op_sel_hi:[1,0]
	v_mul_f32_e32 v19, 0x45800000, v18
	v_lshl_add_u64 v[68:69], v[142:143], 0, s[30:31]
	v_cvt_pk_bf16_f32 v65, v58, v59
	global_store_dwordx4 v[68:69], v[62:65], off offset:0 sc1
	s_nop 1
	v_cvt_pk_bf16_f32 v46, v46, v47
	v_cvt_pk_bf16_f32 v47, v48, v49
	v_cvt_pk_bf16_f32 v48, v42, v43
	v_max_f32_e32 v42, 0, v44
	v_max_f32_e32 v43, 0, v45
	v_max_f32_e32 v30, 0, v30
	v_max_f32_e32 v31, 0, v31
	v_max_f32_e32 v32, 0, v32
	v_max_f32_e32 v33, 0, v33
	v_max_f32_e32 v26, 0, v26
	v_max_f32_e32 v27, 0, v27
	v_cndmask_b32_e32 v18, v18, v19, vcc
	global_store_dwordx4 v[68:69], v[54:57], off offset:0x100 sc1
	s_nop 1
	s_mov_b64 s[30:31], 0x120000
	v_pk_mul_f32 v[42:43], v[42:43], v[42:43]
	v_pk_mul_f32 v[30:31], v[30:31], v[30:31]
	v_pk_mul_f32 v[32:33], v[32:33], v[32:33]
	v_pk_mul_f32 v[28:29], v[28:29], v[34:35] op_sel_hi:[1,0]
	v_pk_mul_f32 v[26:27], v[26:27], v[26:27]
	v_pk_mul_f32 v[16:17], v[16:17], v[18:19] op_sel_hi:[1,0]
	v_pk_mul_f32 v[14:15], v[14:15], v[18:19] op_sel_hi:[1,0]
	v_pk_mul_f32 v[10:11], v[10:11], v[18:19] op_sel_hi:[1,0]
	v_lshl_add_u64 v[52:53], v[142:143], 0, s[30:31]
	v_cvt_pk_bf16_f32 v49, v42, v43
	global_store_dwordx4 v[52:53], v[46:49], off offset:0 sc1
	s_nop 1
	v_cvt_pk_bf16_f32 v30, v30, v31
	v_cvt_pk_bf16_f32 v31, v32, v33
	v_cvt_pk_bf16_f32 v32, v26, v27
	v_max_f32_e32 v26, 0, v28
	v_max_f32_e32 v27, 0, v29
	v_max_f32_e32 v14, 0, v14
	v_max_f32_e32 v15, 0, v15
	v_max_f32_e32 v16, 0, v16
	v_max_f32_e32 v17, 0, v17
	v_max_f32_e32 v10, 0, v10
	v_max_f32_e32 v11, 0, v11
	v_pk_mul_f32 v[8:9], v[8:9], v[18:19] op_sel_hi:[1,0]
	v_pk_mul_f32 v[6:7], v[6:7], v[18:19] op_sel_hi:[1,0]
	v_pk_mul_f32 v[2:3], v[2:3], v[18:19] op_sel_hi:[1,0]
	global_store_dwordx4 v[52:53], v[38:41], off offset:0x100 sc1
	s_nop 1
	s_mov_b64 s[30:31], 0x140000
	v_pk_mul_f32 v[26:27], v[26:27], v[26:27]
	v_pk_mul_f32 v[14:15], v[14:15], v[14:15]
	v_pk_mul_f32 v[16:17], v[16:17], v[16:17]
	v_pk_mul_f32 v[12:13], v[12:13], v[18:19] op_sel_hi:[1,0]
	v_pk_mul_f32 v[10:11], v[10:11], v[10:11]
	v_max_f32_e32 v6, 0, v6
	v_max_f32_e32 v7, 0, v7
	v_max_f32_e32 v8, 0, v8
	v_max_f32_e32 v9, 0, v9
	v_max_f32_e32 v2, 0, v2
	v_max_f32_e32 v3, 0, v3
	v_lshl_add_u64 v[36:37], v[142:143], 0, s[30:31]
	v_cvt_pk_bf16_f32 v33, v26, v27
	global_store_dwordx4 v[36:37], v[30:33], off offset:0 sc1
	s_nop 1
	v_cvt_pk_bf16_f32 v14, v14, v15
	v_cvt_pk_bf16_f32 v15, v16, v17
	v_cvt_pk_bf16_f32 v16, v10, v11
	v_max_f32_e32 v10, 0, v12
	v_max_f32_e32 v11, 0, v13
	v_pk_mul_f32 v[6:7], v[6:7], v[6:7]
	v_pk_mul_f32 v[8:9], v[8:9], v[8:9]
	v_pk_mul_f32 v[4:5], v[4:5], v[18:19] op_sel_hi:[1,0]
	v_pk_mul_f32 v[2:3], v[2:3], v[2:3]
	global_store_dwordx4 v[36:37], v[22:25], off offset:0x100 sc1
	s_nop 1
	s_mov_b64 s[30:31], 0x160000
	v_pk_mul_f32 v[10:11], v[10:11], v[10:11]
	v_cvt_pk_bf16_f32 v6, v6, v7
	v_cvt_pk_bf16_f32 v7, v8, v9
	v_cvt_pk_bf16_f32 v8, v2, v3
	v_max_f32_e32 v2, 0, v4
	v_max_f32_e32 v3, 0, v5
	v_lshl_add_u64 v[20:21], v[142:143], 0, s[30:31]
	v_cvt_pk_bf16_f32 v17, v10, v11
	global_store_dwordx4 v[20:21], v[14:17], off offset:0 sc1
	s_nop 1
	v_pk_mul_f32 v[2:3], v[2:3], v[2:3]
	s_mov_b64 s[30:31], -1
	v_cvt_pk_bf16_f32 v9, v2, v3
	global_store_dwordx4 v[20:21], v[6:9], off offset:0x100 sc1
	s_nop 1
	s_andn2_b64 vcc, exec, s[8:9]
	s_cbranch_vccnz .LBB0_853
	s_andn2_b64 vcc, exec, s[16:17]
	s_cbranch_vccnz .LBB0_852
	s_branch .LBB0_852
